# attention loop: K-fragment LDS reads of both qkt blocks software-pipelined one step ahead (alternate fragment buffer for even steps, counted lgkmcnt waits)
# baseline (speedup 1.0000x reference)
; #define LAS __attribute__((address_space(3)))
; __device__ __forceinline__ void finishSM(f32x16& p0, f32x16& p1, float alpha, float& l_reg, bf16x8& pa0, bf16x8& pa1, bf16x8& pa2, bf16x8& pa3) {
; #pragma unroll
;     for (int r = 0; r < 16; ++r) p1[r] = __builtin_amdgcn_exp2f(p1[r]);
;     float ps = 0;
; #pragma unroll
;     for (int r = 0; r < 16; ++r) ps += p0[r];
; #pragma unroll
;     for (int r = 0; r < 16; ++r) ps += p1[r];
;     { auto rr = __builtin_amdgcn_permlane32_swap(__float_as_uint(ps), __float_as_uint(ps), false, false);
;       ps = __uint_as_float(rr[0]) + __uint_as_float(rr[1]); }
;     l_reg = l_reg * alpha + ps;
;     ...
;     PK4(p0, 0, pa0); PK4(p0, 8, pa1); PK4(p1, 0, pa2); PK4(p1, 8, pa3);
; template <int KB>
; __device__ __forceinline__ void qkt(f32x16& p0, f32x16& p1, lptr K_lds, int r32, int hi, const bf16x8* qr) {
;     p0 = f32x16{}; p1 = f32x16{};
;     lptr kb[4];
; #pragma unroll
;     for (int dd = 0; dd < 4; ++dd) kb[dd] = K_lds + KB * SHM_K + KSWZ(r32, (dd * 16 + hi * 8) * 2);
; #pragma unroll
;     for (int d0 = 0; d0 < 8; ++d0) { lptr a = kb[d0 & 3] + (d0 >> 2) * 128;
;         bf16x8 b0 = *reinterpret_cast<const LAS bf16x8*>(a);
;         bf16x8 b1 = *reinterpret_cast<const LAS bf16x8*>(a + 32 * 256);
;         p0 = __builtin_amdgcn_mfma_f32_32x32x16_bf16(b0, qr[d0], p0, 0, 0, 0);
;         p1 = __builtin_amdgcn_mfma_f32_32x32x16_bf16(b1, qr[d0], p1, 0, 0, 0); }
; }
.LBB0_865:
	ds_read_b128 v[82:85], v187 offset:49152
	ds_read_b128 v[86:89], v187 offset:57344
	ds_read_b128 v[228:231], v185 offset:49152
	ds_read_b128 v[232:235], v185 offset:57344
	ds_read_b128 v[236:239], v184 offset:49152
	ds_read_b128 v[240:243], v184 offset:57344
	v_exp_f32_e32 v80, v80
	v_exp_f32_e32 v1, v1
	s_waitcnt lgkmcnt(5)
	v_mfma_f32_32x32x16_bf16 v[98:113], v[82:85], v[142:145], 0
	v_exp_f32_e32 v78, v78
	v_exp_f32_e32 v79, v79
	v_exp_f32_e32 v76, v76
	v_exp_f32_e32 v77, v77
	v_exp_f32_e32 v81, v74
	v_exp_f32_e32 v146, v75
	v_exp_f32_e32 v226, v72
	s_waitcnt lgkmcnt(4)
	v_mfma_f32_32x32x16_bf16 v[82:97], v[86:89], v[142:145], 0
	s_waitcnt lgkmcnt(2)
	v_mfma_f32_32x32x16_bf16 v[82:97], v[232:235], v[138:141], v[82:97]
	s_waitcnt lgkmcnt(3)
	v_mfma_f32_32x32x16_bf16 v[98:113], v[228:231], v[138:141], v[98:113]
	ds_read_b128 v[228:231], v183 offset:49152
	ds_read_b128 v[232:235], v183 offset:57344
	s_waitcnt lgkmcnt(2)
	v_mfma_f32_32x32x16_bf16 v[82:97], v[240:243], v[134:137], v[82:97]
	s_waitcnt lgkmcnt(3)
	v_mfma_f32_32x32x16_bf16 v[98:113], v[236:239], v[134:137], v[98:113]
	ds_read_b128 v[236:239], v187 offset:49280
	ds_read_b128 v[240:243], v187 offset:57472
	s_waitcnt lgkmcnt(2)
	v_mfma_f32_32x32x16_bf16 v[82:97], v[232:235], v[130:133], v[82:97]
	s_waitcnt lgkmcnt(3)
	v_mfma_f32_32x32x16_bf16 v[98:113], v[228:231], v[130:133], v[98:113]
	ds_read_b128 v[228:231], v185 offset:49280
	ds_read_b128 v[232:235], v185 offset:57472
	s_waitcnt lgkmcnt(2)
	v_mfma_f32_32x32x16_bf16 v[82:97], v[240:243], v[126:129], v[82:97]
	s_waitcnt lgkmcnt(3)
	v_mfma_f32_32x32x16_bf16 v[98:113], v[236:239], v[126:129], v[98:113]
	ds_read_b128 v[236:239], v184 offset:49280
	ds_read_b128 v[240:243], v184 offset:57472
	s_waitcnt lgkmcnt(2)
	v_mfma_f32_32x32x16_bf16 v[82:97], v[232:235], v[122:125], v[82:97]
	s_waitcnt lgkmcnt(3)
	v_mfma_f32_32x32x16_bf16 v[98:113], v[228:231], v[122:125], v[98:113]
	ds_read_b128 v[228:231], v183 offset:49280
	ds_read_b128 v[232:235], v183 offset:57472
	s_waitcnt lgkmcnt(2)
	v_mfma_f32_32x32x16_bf16 v[82:97], v[240:243], v[118:121], v[82:97]
	s_waitcnt lgkmcnt(3)
	v_mfma_f32_32x32x16_bf16 v[98:113], v[236:239], v[118:121], v[98:113]
	s_waitcnt lgkmcnt(0)
	v_mfma_f32_32x32x16_bf16 v[82:97], v[232:235], v[114:117], v[82:97]
	v_exp_f32_e32 v233, v66
	v_add_f32_e32 v66, 0, v160
	v_add_f32_e32 v66, v227, v66
	v_add_f32_e32 v66, v158, v66
	v_add_f32_e32 v66, v161, v66
	v_add_f32_e32 v66, v157, v66
	v_add_f32_e32 v66, v159, v66
	v_add_f32_e32 v66, v155, v66
	v_add_f32_e32 v66, v156, v66
	v_add_f32_e32 v66, v152, v66
	v_add_f32_e32 v66, v154, v66
	v_add_f32_e32 v66, v151, v66
	v_add_f32_e32 v66, v153, v66
	v_add_f32_e32 v66, v148, v66
	v_add_f32_e32 v66, v150, v66
	v_add_f32_e32 v66, v147, v66
	v_add_f32_e32 v66, v149, v66
	v_add_f32_e32 v66, v80, v66
	v_add_f32_e32 v66, v1, v66
	v_add_f32_e32 v66, v78, v66
	v_add_f32_e32 v66, v79, v66
	v_add_f32_e32 v66, v76, v66
	s_waitcnt lgkmcnt(1)
	v_mfma_f32_32x32x16_bf16 v[98:113], v[228:231], v[114:117], v[98:113]
	v_exp_f32_e32 v228, v73
	v_add_f32_e32 v66, v77, v66
	v_exp_f32_e32 v229, v70
	v_add_f32_e32 v66, v81, v66
	v_exp_f32_e32 v230, v71
	v_add_f32_e32 v66, v146, v66
	v_exp_f32_e32 v231, v68
	v_add_f32_e32 v66, v226, v66
	v_exp_f32_e32 v232, v69
	v_add_f32_e32 v66, v228, v66
	v_add_f32_e32 v66, v229, v66
	v_exp_f32_e32 v234, v67
	v_add_f32_e32 v66, v230, v66
	v_add_f32_e32 v66, v231, v66
	v_add_f32_e32 v66, v232, v66
	v_add_f32_e32 v66, v233, v66
	v_add_f32_e32 v224, v234, v66
	v_mov_b32_e32 v225, v224
	v_cvt_pk_bf16_f32 v66, v160, v227
	v_cvt_pk_bf16_f32 v67, v158, v161
	v_cvt_pk_bf16_f32 v68, v157, v159
	v_cvt_pk_bf16_f32 v69, v155, v156
	v_cvt_pk_bf16_f32 v70, v152, v154
	v_cvt_pk_bf16_f32 v71, v151, v153
	v_cvt_pk_bf16_f32 v72, v148, v150
	v_cvt_pk_bf16_f32 v73, v147, v149
	v_cvt_pk_bf16_f32 v74, v80, v1
	v_cvt_pk_bf16_f32 v75, v78, v79
	v_cvt_pk_bf16_f32 v76, v76, v77
	v_cvt_pk_bf16_f32 v77, v81, v146
	v_cvt_pk_bf16_f32 v78, v226, v228
	v_cvt_pk_bf16_f32 v79, v229, v230
	v_cvt_pk_bf16_f32 v80, v231, v232
	v_cvt_pk_bf16_f32 v81, v233, v234
	s_nop 1
	v_permlane32_swap_b32_e32 v224, v225
	v_permlane32_swap_b32_e32 v66, v68
	v_permlane32_swap_b32_e32 v67, v69
	v_permlane32_swap_b32_e32 v70, v72
	v_permlane32_swap_b32_e32 v71, v73
	v_permlane32_swap_b32_e32 v74, v76
	v_permlane32_swap_b32_e32 v75, v77
	v_permlane32_swap_b32_e32 v78, v80
	v_permlane32_swap_b32_e32 v79, v81
	v_add_u32_e32 v227, s89, v186
	v_add_u32_e32 v146, 1, v227
	v_add_u32_e32 v148, 33, v227
	v_ashrrev_i32_e32 v147, 31, v146
	v_ashrrev_i32_e32 v149, 31, v148
	v_lshlrev_b64 v[154:155], 8, v[146:147]
	v_lshlrev_b64 v[156:157], 8, v[148:149]
	v_lshl_add_u64 v[146:147], v[176:177], 0, v[154:155]
	v_lshl_add_u64 v[150:151], v[176:177], 0, v[156:157]
	v_lshl_add_u64 v[154:155], v[178:179], 0, v[154:155]
	v_lshl_add_u64 v[158:159], v[178:179], 0, v[156:157]
	global_load_dwordx4 v[146:149], v[146:147], off
	s_nop 0
	global_load_dwordx4 v[150:153], v[150:151], off
	s_nop 0
	global_load_dwordx4 v[154:157], v[154:155], off
	s_nop 0
	global_load_dwordx4 v[158:161], v[158:159], off
	ds_read_b64_tr_b16 v[228:229], v181 offset:0
	ds_read_b64_tr_b16 v[230:231], v181 offset:0x800
	ds_read_b64_tr_b16 v[232:233], v181 offset:0x1000
	ds_read_b64_tr_b16 v[234:235], v181 offset:0x1800
	ds_read_b64_tr_b16 v[236:237], v181 offset:0x2000
	ds_read_b64_tr_b16 v[238:239], v181 offset:0x2800
	ds_read_b64_tr_b16 v[240:241], v181 offset:0x3000
	ds_read_b64_tr_b16 v[242:243], v181 offset:0x3800
	s_waitcnt lgkmcnt(0)
; #define LAS __attribute__((address_space(3)))
; __device__ __forceinline__ void bias_tile(f32x16& p0, f32x16& p1, const LAS float* cs) {
; #pragma unroll
;     for (int i = 0; i < 4; ++i) { const f32x4 a = *(const LAS f32x4*)(cs + 8 * i), b = *(const LAS f32x4*)(cs + 32 + 8 * i);
; #pragma unroll
;         for (int j = 0; j < 4; ++j) { p0[4 * i + j] = fmaf(p0[4 * i + j], C2, a[j]); p1[4 * i + j] = fmaf(p1[4 * i + j], C2, b[j]); } }
; }
; template <int VB>
; __device__ __forceinline__ void pv_tile(f32x16* o, int vb0, bf16x8 pa0, bf16x8 pa1, bf16x8 pa2, bf16x8 pa3) {
;     ...
;     PV_D0(0); PV_D0(1); PV_D0(2); PV_D0(3);
;     ...
; }
	s_nop 0
	v_mfma_f32_32x32x16_bf16 v[50:65], v[66:69], v[228:231], v[50:65]
	ds_read_b64_tr_b16 v[228:229], v181 offset:0x200
	ds_read_b64_tr_b16 v[230:231], v181 offset:0xa00
	v_mfma_f32_32x32x16_bf16 v[50:65], v[70:73], v[232:235], v[50:65]
	ds_read_b64_tr_b16 v[232:233], v181 offset:0x1200
	ds_read_b64_tr_b16 v[234:235], v181 offset:0x1a00
	v_mfma_f32_32x32x16_bf16 v[50:65], v[74:77], v[236:239], v[50:65]
	ds_read_b64_tr_b16 v[236:237], v181 offset:0x2200
	ds_read_b64_tr_b16 v[238:239], v181 offset:0x2a00
	v_mfma_f32_32x32x16_bf16 v[50:65], v[78:81], v[240:243], v[50:65]
	ds_read_b64_tr_b16 v[240:241], v181 offset:0x3200
	ds_read_b64_tr_b16 v[242:243], v181 offset:0x3a00
	s_waitcnt lgkmcnt(0)
	v_mfma_f32_32x32x16_bf16 v[34:49], v[66:69], v[228:231], v[34:49]
	ds_read_b64_tr_b16 v[228:229], v181 offset:0x400
	ds_read_b64_tr_b16 v[230:231], v181 offset:0xc00
	v_mfma_f32_32x32x16_bf16 v[34:49], v[70:73], v[232:235], v[34:49]
	ds_read_b64_tr_b16 v[232:233], v181 offset:0x1400
	ds_read_b64_tr_b16 v[234:235], v181 offset:0x1c00
	v_mfma_f32_32x32x16_bf16 v[34:49], v[74:77], v[236:239], v[34:49]
	ds_read_b64_tr_b16 v[236:237], v181 offset:0x2400
	ds_read_b64_tr_b16 v[238:239], v181 offset:0x2c00
	v_mfma_f32_32x32x16_bf16 v[34:49], v[78:81], v[240:243], v[34:49]
	ds_read_b64_tr_b16 v[240:241], v181 offset:0x3400
	ds_read_b64_tr_b16 v[242:243], v181 offset:0x3c00
	s_waitcnt lgkmcnt(0)
	v_mfma_f32_32x32x16_bf16 v[18:33], v[66:69], v[228:231], v[18:33]
	ds_read_b64_tr_b16 v[228:229], v181 offset:0x600
	ds_read_b64_tr_b16 v[230:231], v181 offset:0xe00
	v_mfma_f32_32x32x16_bf16 v[18:33], v[70:73], v[232:235], v[18:33]
	ds_read_b64_tr_b16 v[232:233], v181 offset:0x1600
	ds_read_b64_tr_b16 v[234:235], v181 offset:0x1e00
	v_mfma_f32_32x32x16_bf16 v[18:33], v[74:77], v[236:239], v[18:33]
	ds_read_b64_tr_b16 v[236:237], v181 offset:0x2600
	ds_read_b64_tr_b16 v[238:239], v181 offset:0x2e00
	v_mfma_f32_32x32x16_bf16 v[18:33], v[78:81], v[240:243], v[18:33]
	ds_read_b64_tr_b16 v[240:241], v181 offset:0x3600
	ds_read_b64_tr_b16 v[242:243], v181 offset:0x3e00
	s_waitcnt lgkmcnt(0)
	v_mfma_f32_32x32x16_bf16 v[2:17], v[66:69], v[228:231], v[2:17]
	s_cmp_le_i32 s89, s80
	v_mfma_f32_32x32x16_bf16 v[2:17], v[70:73], v[232:235], v[2:17]
	v_mfma_f32_32x32x16_bf16 v[2:17], v[74:77], v[236:239], v[2:17]
	v_mfma_f32_32x32x16_bf16 v[2:17], v[78:81], v[240:243], v[2:17]
	ds_read_b128 v[228:231], v223 offset:128
	ds_read_b128 v[78:81], v223
	ds_read_b128 v[70:73], v223 offset:32
	ds_read_b128 v[232:235], v223 offset:160
	ds_read_b128 v[74:77], v223 offset:64
	ds_read_b128 v[236:239], v223 offset:192
	ds_read_b128 v[240:243], v223 offset:96
	ds_read_b128 v[244:247], v223 offset:224
	s_waitcnt lgkmcnt(6)
	v_pk_fma_f32 v[100:101], v[100:101], s[2:3], v[80:81] op_sel_hi:[1,0,1]
	s_waitcnt lgkmcnt(3)
	v_pk_fma_f32 v[68:69], v[106:107], s[2:3], v[74:75] op_sel_hi:[1,0,1]
	v_pk_fma_f32 v[74:75], v[102:103], s[2:3], v[70:71] op_sel_hi:[1,0,1]
	s_waitcnt lgkmcnt(1)
	v_pk_fma_f32 v[66:67], v[110:111], s[2:3], v[240:241] op_sel_hi:[1,0,1]
	v_pk_fma_f32 v[70:71], v[112:113], s[2:3], v[242:243] op_sel_hi:[1,0,1]
	v_pk_fma_f32 v[76:77], v[108:109], s[2:3], v[76:77] op_sel_hi:[1,0,1]
	v_pk_fma_f32 v[102:103], v[104:105], s[2:3], v[72:73] op_sel_hi:[1,0,1]
	v_pk_fma_f32 v[98:99], v[98:99], s[2:3], v[78:79] op_sel_hi:[1,0,1]
	s_waitcnt lgkmcnt(0)
	v_pk_fma_f32 v[72:73], v[94:95], s[2:3], v[244:245] op_sel_hi:[1,0,1]
	v_pk_fma_f32 v[78:79], v[90:91], s[2:3], v[236:237] op_sel_hi:[1,0,1]
	v_pk_fma_f32 v[86:87], v[86:87], s[2:3], v[232:233] op_sel_hi:[1,0,1]
	v_pk_fma_f32 v[80:81], v[96:97], s[2:3], v[246:247] op_sel_hi:[1,0,1]
	v_pk_fma_f32 v[90:91], v[92:93], s[2:3], v[238:239] op_sel_hi:[1,0,1]
	v_pk_fma_f32 v[88:89], v[88:89], s[2:3], v[234:235] op_sel_hi:[1,0,1]
	v_pk_fma_f32 v[84:85], v[84:85], s[2:3], v[230:231] op_sel_hi:[1,0,1]
	v_pk_fma_f32 v[82:83], v[82:83], s[2:3], v[228:229] op_sel_hi:[1,0,1]
	s_cbranch_scc1 .LBB0_867
; __device__ __forceinline__ void mask_tile(f32x16& p0, f32x16& p1, int dq) {
;     const float NEG = -__builtin_inff();
; #pragma unroll
;     for (int r = 0; r < 16; ++r) { const int c = (r & 3) + 8 * (r >> 2);
;         if (dq - c < 0) p0[r] = NEG;
;         if (dq - c - 32 < 0) p1[r] = NEG; }
; }
	v_add_u32_e32 v1, 64, v222
	v_cmp_gt_i32_e64 s[70:71], 26, v1
	v_cmp_gt_i32_e64 s[72:73], 27, v1
	v_cmp_gt_i32_e64 s[68:69], 25, v1
	s_and_b64 s[70:71], s[72:73], s[70:71]
	v_cmp_gt_i32_e64 s[66:67], 24, v1
	s_and_b64 s[68:69], s[70:71], s[68:69]
	v_cmp_gt_i32_e64 s[64:65], 19, v1
	s_and_b64 s[66:67], s[68:69], s[66:67]
	v_cmp_gt_i32_e64 s[62:63], 18, v1
	s_and_b64 s[64:65], s[66:67], s[64:65]
	v_cmp_gt_i32_e64 s[60:61], 17, v1
	s_and_b64 s[62:63], s[64:65], s[62:63]
	v_cmp_gt_i32_e64 s[58:59], 16, v1
	s_and_b64 s[60:61], s[62:63], s[60:61]
	v_cmp_gt_i32_e64 s[56:57], 11, v1
	s_and_b64 s[58:59], s[60:61], s[58:59]
	v_cmp_gt_i32_e64 s[54:55], 10, v1
	s_and_b64 s[56:57], s[58:59], s[56:57]
	v_cmp_gt_i32_e64 s[52:53], 9, v1
	s_and_b64 s[54:55], s[56:57], s[54:55]
	v_cmp_gt_i32_e64 s[50:51], 8, v1
	s_and_b64 s[52:53], s[54:55], s[52:53]
	v_cmp_gt_i32_e64 s[48:49], 3, v1
	s_and_b64 s[50:51], s[52:53], s[50:51]
	v_cmp_gt_i32_e64 s[46:47], 2, v1
	s_and_b64 s[48:49], s[50:51], s[48:49]
	v_cmp_gt_i32_e64 s[44:45], 1, v1
	s_and_b64 s[46:47], s[48:49], s[46:47]
	v_cmp_gt_i32_e64 s[42:43], 0, v1
	s_and_b64 s[44:45], s[46:47], s[44:45]
	s_and_b64 s[42:43], s[44:45], s[42:43]
	v_cmp_gt_i32_e64 s[38:39], 58, v1
	v_cndmask_b32_e64 v98, v98, v206, s[42:43]
	v_cmp_gt_i32_e64 s[42:43], 59, v1
	v_cmp_gt_i32_e64 s[36:37], 57, v1
	s_and_b64 s[38:39], s[42:43], s[38:39]
	v_cmp_gt_i32_e64 s[34:35], 56, v1
	s_and_b64 s[36:37], s[38:39], s[36:37]
	v_cmp_gt_i32_e64 s[30:31], 51, v1
	s_and_b64 s[34:35], s[36:37], s[34:35]
	v_cmp_gt_i32_e64 s[28:29], 50, v1
	s_and_b64 s[30:31], s[34:35], s[30:31]
	v_cmp_gt_i32_e64 s[26:27], 49, v1
	s_and_b64 s[28:29], s[30:31], s[28:29]
	v_cmp_gt_i32_e64 s[24:25], 48, v1
	s_and_b64 s[26:27], s[28:29], s[26:27]
	v_cmp_gt_i32_e64 s[22:23], 43, v1
	s_and_b64 s[24:25], s[26:27], s[24:25]
	v_cmp_gt_i32_e64 s[20:21], 42, v1
	s_and_b64 s[22:23], s[24:25], s[22:23]
	v_cmp_gt_i32_e64 s[18:19], 41, v1
	s_and_b64 s[20:21], s[22:23], s[20:21]
	v_cmp_gt_i32_e64 s[16:17], 40, v1
	s_and_b64 s[18:19], s[20:21], s[18:19]
	v_cmp_gt_i32_e64 s[14:15], 35, v1
	s_and_b64 s[16:17], s[18:19], s[16:17]
	v_cmp_gt_i32_e64 s[12:13], 34, v1
	s_and_b64 s[14:15], s[16:17], s[14:15]
	v_cmp_gt_i32_e64 s[10:11], 33, v1
	s_and_b64 s[12:13], s[14:15], s[12:13]
	v_cmp_gt_i32_e32 vcc, 32, v1
	s_and_b64 s[10:11], s[12:13], s[10:11]
	s_and_b64 vcc, s[10:11], vcc
	v_cndmask_b32_e64 v71, v71, v206, s[72:73]
	v_cndmask_b32_e64 v70, v70, v206, s[70:71]
	v_cndmask_b32_e64 v67, v67, v206, s[68:69]
	v_cndmask_b32_e64 v66, v66, v206, s[66:67]
	v_cndmask_b32_e64 v77, v77, v206, s[64:65]
	v_cndmask_b32_e64 v76, v76, v206, s[62:63]
	v_cndmask_b32_e64 v69, v69, v206, s[60:61]
	v_cndmask_b32_e64 v68, v68, v206, s[58:59]
	v_cndmask_b32_e64 v103, v103, v206, s[56:57]
	v_cndmask_b32_e64 v102, v102, v206, s[54:55]
	v_cndmask_b32_e64 v75, v75, v206, s[52:53]
	v_cndmask_b32_e64 v74, v74, v206, s[50:51]
	v_cndmask_b32_e64 v101, v101, v206, s[48:49]
	v_cndmask_b32_e64 v100, v100, v206, s[46:47]
	v_cndmask_b32_e64 v99, v99, v206, s[44:45]
	v_cndmask_b32_e64 v81, v81, v206, s[42:43]
	v_cndmask_b32_e64 v80, v80, v206, s[38:39]
	v_cndmask_b32_e64 v73, v73, v206, s[36:37]
	v_cndmask_b32_e64 v72, v72, v206, s[34:35]
	v_cndmask_b32_e64 v91, v91, v206, s[30:31]
	v_cndmask_b32_e64 v90, v90, v206, s[28:29]
	v_cndmask_b32_e64 v79, v79, v206, s[26:27]
	v_cndmask_b32_e64 v78, v78, v206, s[24:25]
	v_cndmask_b32_e64 v89, v89, v206, s[22:23]
	v_cndmask_b32_e64 v88, v88, v206, s[20:21]
	v_cndmask_b32_e64 v87, v87, v206, s[18:19]
	v_cndmask_b32_e64 v86, v86, v206, s[16:17]
	v_cndmask_b32_e64 v85, v85, v206, s[14:15]
	v_cndmask_b32_e64 v84, v84, v206, s[12:13]
	v_cndmask_b32_e64 v83, v83, v206, s[10:11]
	v_cndmask_b32_e32 v82, v82, v206, vcc

; #define LAS __attribute__((address_space(3)))
; __device__ __forceinline__ void partialSM(f32x16& p0, f32x16& p1, float& m_reg, float& alpha) {
;     float pmax = p0[0];
; #pragma unroll
;     for (int r = 1; r < 16; ++r) pmax = fmaxf(pmax, p0[r]);
; #pragma unroll
;     for (int r = 0; r < 16; ++r) pmax = fmaxf(pmax, p1[r]);
;     { auto rr = __builtin_amdgcn_permlane32_swap(__float_as_uint(pmax), __float_as_uint(pmax), false, false);
;       pmax = fmaxf(__uint_as_float(rr[0]), __uint_as_float(rr[1])); }
;     float mn;
;     if (__builtin_expect(__all(pmax - m_reg <= THR2), 1)) { mn = m_reg; alpha = 1.f; }
;     else { mn = fmaxf(m_reg, pmax); alpha = __builtin_amdgcn_exp2f(m_reg - mn); m_reg = mn; }
; #pragma unroll
;     for (int r = 0; r < 16; ++r) p0[r] = p0[r] - mn;
; #pragma unroll
;     for (int r = 0; r < 16; ++r) p1[r] = p1[r] - mn;
; #pragma unroll
;     for (int r = 0; r < 16; ++r) p0[r] = __builtin_amdgcn_exp2f(p0[r]);
; }
; __device__ __forceinline__ void finishSM(f32x16& p0, f32x16& p1, float alpha, float& l_reg, bf16x8& pa0, bf16x8& pa1, bf16x8& pa2, bf16x8& pa3) {
; #pragma unroll
;     for (int r = 0; r < 16; ++r) p1[r] = __builtin_amdgcn_exp2f(p1[r]);
;     float ps = 0;
; #pragma unroll
;     for (int r = 0; r < 16; ++r) ps += p0[r];
; #pragma unroll
;     for (int r = 0; r < 16; ++r) ps += p1[r];
;     { auto rr = __builtin_amdgcn_permlane32_swap(__float_as_uint(ps), __float_as_uint(ps), false, false);
;       ps = __uint_as_float(rr[0]) + __uint_as_float(rr[1]); }
;     l_reg = l_reg * alpha + ps;
;     ...
;     PK4(p0, 0, pa0); PK4(p0, 8, pa1); PK4(p1, 0, pa2); PK4(p1, 8, pa3);
; template <int KB>
; __device__ __forceinline__ void qkt(f32x16& p0, f32x16& p1, lptr K_lds, int r32, int hi, const bf16x8* qr) {
;     p0 = f32x16{}; p1 = f32x16{};
;     lptr kb[4];
; #pragma unroll
;     for (int dd = 0; dd < 4; ++dd) kb[dd] = K_lds + KB * SHM_K + KSWZ(r32, (dd * 16 + hi * 8) * 2);
; #pragma unroll
;     for (int d0 = 0; d0 < 8; ++d0) { lptr a = kb[d0 & 3] + (d0 >> 2) * 128;
;         bf16x8 b0 = *reinterpret_cast<const LAS bf16x8*>(a);
;         bf16x8 b1 = *reinterpret_cast<const LAS bf16x8*>(a + 32 * 256);
;         p0 = __builtin_amdgcn_mfma_f32_32x32x16_bf16(b0, qr[d0], p0, 0, 0, 0);
;         p1 = __builtin_amdgcn_mfma_f32_32x32x16_bf16(b1, qr[d0], p1, 0, 0, 0); }
; }
.LBB0_871:
	v_cndmask_b32_e64 v1, v1, v220, s[10:11]
	v_sub_f32_e32 v92, v98, v1
	v_sub_f32_e32 v93, v99, v1
	v_sub_f32_e32 v94, v100, v1
	v_sub_f32_e32 v95, v101, v1
	v_sub_f32_e32 v74, v74, v1
	v_sub_f32_e32 v75, v75, v1
	v_sub_f32_e32 v96, v102, v1
	v_sub_f32_e32 v97, v103, v1
	v_sub_f32_e32 v68, v68, v1
	v_sub_f32_e32 v69, v69, v1
	v_sub_f32_e32 v76, v76, v1
	v_sub_f32_e32 v77, v77, v1
	v_sub_f32_e32 v66, v66, v1
	v_sub_f32_e32 v67, v67, v1
	v_sub_f32_e32 v70, v70, v1
	v_sub_f32_e32 v71, v71, v1
	v_exp_f32_e32 v98, v92
	v_exp_f32_e32 v113, v93
	v_exp_f32_e32 v99, v94
	v_exp_f32_e32 v112, v95
	v_exp_f32_e32 v100, v74
	v_exp_f32_e32 v111, v75
	v_exp_f32_e32 v101, v96
	v_exp_f32_e32 v110, v97
	v_exp_f32_e32 v102, v68
	v_exp_f32_e32 v109, v69
	v_exp_f32_e32 v103, v76
	v_exp_f32_e32 v108, v77
	v_exp_f32_e32 v104, v66
	v_exp_f32_e32 v107, v67
	v_exp_f32_e32 v105, v70
	v_exp_f32_e32 v106, v71
	v_sub_f32_e32 v220, v82, v1
	v_sub_f32_e32 v236, v83, v1
	v_sub_f32_e32 v237, v84, v1
	v_sub_f32_e32 v238, v85, v1
	v_sub_f32_e32 v239, v86, v1
	v_sub_f32_e32 v240, v87, v1
	v_sub_f32_e32 v241, v88, v1
	v_sub_f32_e32 v242, v89, v1
	v_sub_f32_e32 v243, v78, v1
	v_sub_f32_e32 v244, v79, v1
	v_sub_f32_e32 v245, v90, v1
	v_sub_f32_e32 v246, v91, v1
	v_sub_f32_e32 v247, v72, v1
	v_sub_f32_e32 v248, v73, v1
	v_sub_f32_e32 v249, v80, v1
	v_sub_f32_e32 v250, v81, v1
	s_waitcnt lgkmcnt(0)
	s_barrier
	ds_read_b128 v[66:69], v187 offset:32768
	ds_read_b128 v[70:73], v187 offset:40960
	ds_read_b128 v[228:231], v185 offset:32768
	ds_read_b128 v[232:235], v185 offset:40960
	ds_read_b128 v[146:149], v184 offset:32768
	ds_read_b128 v[150:153], v184 offset:40960
	v_exp_f32_e32 v220, v220
	s_waitcnt lgkmcnt(5)
	v_mfma_f32_32x32x16_bf16 v[82:97], v[66:69], v[142:145], 0
	s_waitcnt lgkmcnt(4)
	v_mfma_f32_32x32x16_bf16 v[66:81], v[70:73], v[142:145], 0
	s_waitcnt lgkmcnt(3)
	v_mfma_f32_32x32x16_bf16 v[82:97], v[228:231], v[138:141], v[82:97]
	s_waitcnt lgkmcnt(2)
	v_mfma_f32_32x32x16_bf16 v[66:81], v[232:235], v[138:141], v[66:81]
	ds_read_b128 v[228:231], v183 offset:32768
	ds_read_b128 v[232:235], v183 offset:40960
	s_waitcnt lgkmcnt(3)
	v_mfma_f32_32x32x16_bf16 v[82:97], v[146:149], v[134:137], v[82:97]
	s_waitcnt lgkmcnt(2)
	v_mfma_f32_32x32x16_bf16 v[66:81], v[150:153], v[134:137], v[66:81]
	ds_read_b128 v[146:149], v187 offset:32896
	ds_read_b128 v[150:153], v187 offset:41088
	s_waitcnt lgkmcnt(3)
	v_mfma_f32_32x32x16_bf16 v[82:97], v[228:231], v[130:133], v[82:97]
	s_waitcnt lgkmcnt(2)
	v_mfma_f32_32x32x16_bf16 v[66:81], v[232:235], v[130:133], v[66:81]
	ds_read_b128 v[228:231], v185 offset:32896
	ds_read_b128 v[232:235], v185 offset:41088
	s_waitcnt lgkmcnt(3)
	v_mfma_f32_32x32x16_bf16 v[82:97], v[146:149], v[126:129], v[82:97]
	s_waitcnt lgkmcnt(2)
	v_mfma_f32_32x32x16_bf16 v[66:81], v[150:153], v[126:129], v[66:81]
	ds_read_b128 v[146:149], v184 offset:32896
	ds_read_b128 v[150:153], v184 offset:41088
	s_waitcnt lgkmcnt(3)
	v_mfma_f32_32x32x16_bf16 v[82:97], v[228:231], v[122:125], v[82:97]
	s_waitcnt lgkmcnt(2)
	v_mfma_f32_32x32x16_bf16 v[66:81], v[232:235], v[122:125], v[66:81]
	ds_read_b128 v[228:231], v183 offset:32896
	ds_read_b128 v[232:235], v183 offset:41088
	s_waitcnt lgkmcnt(3)
	v_mfma_f32_32x32x16_bf16 v[82:97], v[146:149], v[118:121], v[82:97]
	s_waitcnt lgkmcnt(2)
	v_mfma_f32_32x32x16_bf16 v[66:81], v[150:153], v[118:121], v[66:81]
	s_waitcnt lgkmcnt(1)
	v_mfma_f32_32x32x16_bf16 v[82:97], v[228:231], v[114:117], v[82:97]
	v_add_f32_e32 v228, 0, v98
	v_add_f32_e32 v228, v113, v228
	v_add_f32_e32 v228, v99, v228
	v_add_f32_e32 v228, v112, v228
	v_add_f32_e32 v228, v100, v228
	v_add_f32_e32 v228, v111, v228
	v_add_f32_e32 v228, v101, v228
	v_add_f32_e32 v228, v110, v228
	v_add_f32_e32 v228, v102, v228
	v_add_f32_e32 v228, v109, v228
	v_add_f32_e32 v228, v103, v228
	v_add_f32_e32 v228, v108, v228
	v_add_f32_e32 v228, v104, v228
	v_exp_f32_e32 v230, v236
	v_add_f32_e32 v228, v107, v228
	v_exp_f32_e32 v231, v237
	v_add_f32_e32 v228, v105, v228
	s_waitcnt lgkmcnt(0)
	v_mfma_f32_32x32x16_bf16 v[66:81], v[232:235], v[114:117], v[66:81]
	v_exp_f32_e32 v232, v238
	v_add_f32_e32 v228, v106, v228
	v_exp_f32_e32 v233, v239
	v_add_f32_e32 v228, v220, v228
	v_exp_f32_e32 v234, v240
	v_add_f32_e32 v228, v230, v228
	v_exp_f32_e32 v235, v241
	v_add_f32_e32 v228, v231, v228
	v_exp_f32_e32 v236, v242
	v_add_f32_e32 v228, v232, v228
	v_exp_f32_e32 v237, v243
	v_add_f32_e32 v228, v233, v228
	v_exp_f32_e32 v238, v244
	v_add_f32_e32 v228, v234, v228
	v_exp_f32_e32 v239, v245
	v_add_f32_e32 v228, v235, v228
	v_exp_f32_e32 v240, v246
	v_add_f32_e32 v228, v236, v228
	v_exp_f32_e32 v241, v247
	v_add_f32_e32 v228, v237, v228
	v_exp_f32_e32 v242, v248
	v_add_f32_e32 v228, v238, v228
	v_exp_f32_e32 v243, v249
	v_add_f32_e32 v228, v239, v228
	v_exp_f32_e32 v244, v250
	v_add_f32_e32 v228, v240, v228
	v_add_f32_e32 v228, v241, v228
	v_add_f32_e32 v228, v242, v228
	v_add_f32_e32 v228, v243, v228
	v_add_f32_e32 v228, v244, v228
	v_mov_b32_e32 v229, v228
	v_cvt_pk_bf16_f32 v98, v98, v113
	v_cvt_pk_bf16_f32 v99, v99, v112
	v_cvt_pk_bf16_f32 v100, v100, v111
	v_cvt_pk_bf16_f32 v101, v101, v110
	v_cvt_pk_bf16_f32 v102, v102, v109
	v_cvt_pk_bf16_f32 v103, v103, v108
	v_cvt_pk_bf16_f32 v104, v104, v107
	v_cvt_pk_bf16_f32 v105, v105, v106
	v_cvt_pk_bf16_f32 v106, v220, v230
	v_cvt_pk_bf16_f32 v107, v231, v232
	v_cvt_pk_bf16_f32 v108, v233, v234
	v_cvt_pk_bf16_f32 v109, v235, v236
	v_cvt_pk_bf16_f32 v110, v237, v238
	v_cvt_pk_bf16_f32 v111, v239, v240
	v_cvt_pk_bf16_f32 v112, v241, v242
	v_cvt_pk_bf16_f32 v113, v243, v244
	s_nop 1
	v_permlane32_swap_b32_e32 v228, v229
	v_permlane32_swap_b32_e32 v98, v100
	v_permlane32_swap_b32_e32 v99, v101
	v_permlane32_swap_b32_e32 v102, v104
	v_permlane32_swap_b32_e32 v103, v105
	v_permlane32_swap_b32_e32 v106, v108
	v_permlane32_swap_b32_e32 v107, v109
	v_permlane32_swap_b32_e32 v110, v112
	v_permlane32_swap_b32_e32 v111, v113
	s_add_i32 s10, s88, 1
	s_cmp_lt_i32 s10, s81
	s_cselect_b64 s[40:41], -1, 0
	s_cmp_ge_i32 s10, s81
	s_cbranch_scc1 .LBB0_873
	v_add_u32_e32 v146, 0x41, v227
	v_add_u32_e32 v148, 0x61, v227
	v_ashrrev_i32_e32 v147, 31, v146
	v_ashrrev_i32_e32 v149, 31, v148
	v_lshlrev_b64 v[154:155], 8, v[146:147]
	v_lshlrev_b64 v[156:157], 8, v[148:149]
	v_lshl_add_u64 v[146:147], v[176:177], 0, v[154:155]
	v_lshl_add_u64 v[150:151], v[176:177], 0, v[156:157]
	v_lshl_add_u64 v[154:155], v[178:179], 0, v[154:155]
	v_lshl_add_u64 v[158:159], v[178:179], 0, v[156:157]
	global_load_dwordx4 v[146:149], v[146:147], off
	s_nop 0
	global_load_dwordx4 v[150:153], v[150:151], off
	s_nop 0
	global_load_dwordx4 v[154:157], v[154:155], off
	s_nop 0
	global_load_dwordx4 v[158:161], v[158:159], off
